# MLA loop: next-next tile staged into its LDS ring slot during the exp phase (three groups) instead of in front of the step barrier; rope-chunk store made unconditional via a scratch address
# speedup vs baseline: 1.0011x; 1.0011x over previous
; #define PG8_LAS __attribute__((address_space(3)))
;     DI bf16_t* kv() const { return (bf16_t*)(ws + WS_KV); }
; template <bool MLA> DI void tile_gload(TileRegs& R, const bf16_t* kp, size_t kst, const bf16_t* vp, size_t vst, const bf16_t* k2p, int kb, int tid) {
;     const int key = tid >> 3, c = tid & 7;
;     R.k = *(const u32x4*)(kp + (size_t)(kb + key) * kst + 8 * c);
;     R.v = *(const u32x4*)(vp + (size_t)(kb + (tid & 63)) * vst + 8 * (tid >> 6));
;     if (MLA) R.k2 = *(const u32x4*)(k2p + (size_t)(kb + ((tid & 255) >> 2)) * 32 + 8 * (tid & 3));
; }
; template <bool MLA> DI void tile_lstore(const TileRegs& R, lbf Ks, lbf Vt, int tid) {
;     constexpr int KLD = MLA ? 104 : 72;
;     const int key = tid >> 3, c = tid & 7;
;     *(PG8_LAS u32x4*)(Ks + key * KLD + 8 * c) = R.k;
;     if (MLA) { if (tid < 256) *(PG8_LAS u32x4*)(Ks + (tid >> 2) * KLD + 64 + 8 * (tid & 3)) = R.k2; }
;     { const int kv = tid & 63, cv = tid >> 6, kp = (kv & ~12) | ((kv & 4) << 1) | ((kv & 8) >> 1);
; #pragma unroll
;       for (int j = 0; j < 8; ++j) Vt[(8 * cv + j) * A_VLD + kp] = (bf16_t)(R.v[j >> 1] >> (16 * (j & 1))); }
; }
.Lmla_entry:
	v_add_u32_e32 v129, v129, v0
	v_add_u32_e32 v130, v130, v120
	s_mov_b32 s24, 0xd000
	v_add3_u32 v131, v131, v132, s24
	v_add_u32_e32 v136, 0xd000, v136
	v_lshrrev_b32_e32 v170, 3, v214
	v_and_b32_e32 v176, 7, v214
	v_lshlrev_b32_e32 v176, 4, v176
	v_lshl_add_u32 v118, v170, 11, v176
	v_and_b32_e32 v170, 63, v214
	v_lshrrev_b32_e32 v176, 6, v214
	v_lshlrev_b32_e32 v176, 4, v176
	v_lshl_add_u32 v119, v170, 11, v176
	v_bfe_u32 v170, v214, 2, 6
	v_and_b32_e32 v176, 3, v214
	v_lshlrev_b32_e32 v176, 4, v176
	v_lshl_add_u32 v120, v170, 6, v176
	v_readfirstlane_b32 s10, v122
	v_readfirstlane_b32 s11, v123
	v_readfirstlane_b32 s48, v126
	v_readfirstlane_b32 s49, v127
	s_nop 3
	s_add_u32 s10, s10, 0x40000
	s_addc_u32 s11, s11, 0
	s_add_u32 s48, s48, 0x2000
	s_addc_u32 s49, s49, 0
	global_load_dwordx4 v[106:109], v118, s[10:11]
	global_load_dwordx4 v[102:105], v119, s[10:11] offset:1024
	global_load_dwordx4 v[110:113], v120, s[48:49]
	s_lshr_b32 s16, s22, 6
	s_add_i32 s16, s16, 1
	v_readfirstlane_b32 s22, v128
	s_mov_b32 s17, 0
	s_cmp_lg_u64 s[46:47], 0
	s_cselect_b32 s23, 1, 0
	s_lshr_b32 s22, s22, 6
	s_cmp_eq_u32 s23, 1
	s_cbranch_scc1 .Lmla_rwok
	v_lshlrev_b32_e32 v130, 4, v221
	v_add_u32_e32 v130, 0x16000, v130
.Lmla_rwok:
	ds_read_b128 v[186:189], v135 offset:0
	ds_read_b128 v[190:193], v135 offset:6656
	ds_read_b128 v[194:197], v135 offset:32
	ds_read_b128 v[202:205], v135 offset:6688
	ds_read_b128 v[210:213], v135 offset:64
	ds_read_b128 v[234:237], v135 offset:6720
	s_waitcnt lgkmcnt(5)
	v_mfma_f32_32x32x16_bf16 v[34:49], v[186:189], v[66:69], 0
	s_waitcnt lgkmcnt(4)
	v_mfma_f32_32x32x16_bf16 v[50:65], v[190:193], v[66:69], 0
	ds_read_b128 v[238:241], v135 offset:96
	ds_read_b128 v[242:245], v135 offset:6752
	s_waitcnt lgkmcnt(5)
	v_mfma_f32_32x32x16_bf16 v[34:49], v[194:197], v[70:73], v[34:49]
	s_waitcnt lgkmcnt(4)
	v_mfma_f32_32x32x16_bf16 v[50:65], v[202:205], v[70:73], v[50:65]
	ds_read_b128 v[186:189], v135 offset:128
	ds_read_b128 v[190:193], v135 offset:6784
	s_waitcnt lgkmcnt(5)
	v_mfma_f32_32x32x16_bf16 v[34:49], v[210:213], v[74:77], v[34:49]
	s_waitcnt lgkmcnt(4)
	v_mfma_f32_32x32x16_bf16 v[50:65], v[234:237], v[74:77], v[50:65]
	ds_read_b128 v[194:197], v135 offset:160
	ds_read_b128 v[202:205], v135 offset:6816
	s_waitcnt lgkmcnt(5)
	v_mfma_f32_32x32x16_bf16 v[34:49], v[238:241], v[78:81], v[34:49]
	s_waitcnt lgkmcnt(4)
	v_mfma_f32_32x32x16_bf16 v[50:65], v[242:245], v[78:81], v[50:65]
	s_waitcnt lgkmcnt(3)
	v_mfma_f32_32x32x16_bf16 v[34:49], v[186:189], v[94:97], v[34:49]
	s_waitcnt lgkmcnt(2)
	v_mfma_f32_32x32x16_bf16 v[50:65], v[190:193], v[94:97], v[50:65]
	s_waitcnt lgkmcnt(1)
	v_mfma_f32_32x32x16_bf16 v[34:49], v[194:197], v[98:101], v[34:49]
	s_waitcnt lgkmcnt(0)
	v_mfma_f32_32x32x16_bf16 v[50:65], v[202:205], v[98:101], v[50:65]
	s_waitcnt vmcnt(3)
	ds_write_b128 v129, v[86:89] offset:13312
	ds_write_b128 v130, v[90:93] offset:13440
	ds_write_b16 v131, v82 offset:9216
	ds_write_b16_d16_hi v131, v82 offset:9360
	ds_write_b16 v131, v83 offset:9504
	ds_write_b16_d16_hi v131, v83 offset:9648
	ds_write_b16 v131, v84 offset:9792
	ds_write_b16_d16_hi v131, v84 offset:9936
	ds_write_b16 v131, v85 offset:10080
	ds_write_b16_d16_hi v131, v85 offset:10224
	s_waitcnt lgkmcnt(0)
	s_barrier

; #define PG8_LAS __attribute__((address_space(3)))
;     DI bf16_t* kv() const { return (bf16_t*)(ws + WS_KV); }
; template <bool MLA> DI void tile_lstore(const TileRegs& R, lbf Ks, lbf Vt, int tid) {
;     constexpr int KLD = MLA ? 104 : 72;
;     const int key = tid >> 3, c = tid & 7;
;     *(PG8_LAS u32x4*)(Ks + key * KLD + 8 * c) = R.k;
;     if (MLA) { if (tid < 256) *(PG8_LAS u32x4*)(Ks + (tid >> 2) * KLD + 64 + 8 * (tid & 3)) = R.k2; }
;     { const int kv = tid & 63, cv = tid >> 6, kp = (kv & ~12) | ((kv & 4) << 1) | ((kv & 8) >> 1);
; #pragma unroll
;       for (int j = 0; j < 8; ++j) Vt[(8 * cv + j) * A_VLD + kp] = (bf16_t)(R.v[j >> 1] >> (16 * (j & 1))); }
; }
; template <bool PV> DI void online_step_mx(f32x16& x0, f32x16& x1, float mx, float& m, float& l, f32x16 (&O)[2]) {
;     const float mn = fmaxf(m, mx), alpha = __builtin_amdgcn_exp2f(m - mn);
;     float ls = 0.f;
; #pragma unroll
;     for (int i = 0; i < 16; ++i) { x0[i] = __builtin_amdgcn_exp2f(x0[i] - mn); x1[i] = __builtin_amdgcn_exp2f(x1[i] - mn); ls += x0[i] + x1[i]; }
;     ls += __shfl_xor(ls, 32);
;     l = l * alpha + ls; m = mn;
;     if (PV) { if (__any(alpha != 1.f)) {
; #pragma unroll
;         for (int i = 0; i < 16; ++i) { O[0][i] *= alpha; O[1][i] *= alpha; } } }
; }
.Lmla_rback_f0:
	v_fma_f32 v34, v34, s40, -v137
	v_fma_f32 v35, v35, s40, -v137
	v_fma_f32 v36, v36, s40, -v137
	v_fma_f32 v37, v37, s40, -v137
	s_waitcnt lgkmcnt(4)
	v_mfma_f32_32x32x16_bf16 v[138:153], v[210:213], v[74:77], v[138:153]
	v_exp_f32_e32 v34, v34
	v_exp_f32_e32 v35, v35
	v_exp_f32_e32 v36, v36
	v_exp_f32_e32 v37, v37
	v_fma_f32 v38, v38, s40, -v137
	v_fma_f32 v39, v39, s40, -v137
	v_fma_f32 v40, v40, s40, -v137
	v_mfma_f32_32x32x16_bf16 v[154:169], v[234:237], v[74:77], v[154:169]
	ds_read_b128 v[194:197], v135 offset:13472
	ds_read_b128 v[202:205], v135 offset:20128
	v_fma_f32 v41, v41, s40, -v137
	v_exp_f32_e32 v38, v38
	v_exp_f32_e32 v39, v39
	v_exp_f32_e32 v40, v40
	v_exp_f32_e32 v41, v41
	v_add_f32_e32 v134, v134, v34
	s_waitcnt lgkmcnt(4)
	v_mfma_f32_32x32x16_bf16 v[138:153], v[238:241], v[78:81], v[138:153]
	v_add_f32_e32 v134, v134, v36
	v_add_f32_e32 v177, v35, v37
	v_add_f32_e32 v134, v134, v38
	v_add_f32_e32 v177, v177, v39
	v_add_f32_e32 v134, v134, v40
	v_add_f32_e32 v177, v177, v41
	v_cvt_pk_bf16_f32 v34, v34, v35
	v_mfma_f32_32x32x16_bf16 v[154:169], v[242:245], v[78:81], v[154:169]
	ds_read_b128 v[210:213], v136 offset:0
	ds_read_b128 v[234:237], v136 offset:4608
	v_cvt_pk_bf16_f32 v35, v36, v37
	v_cvt_pk_bf16_f32 v36, v38, v39
	v_cvt_pk_bf16_f32 v37, v40, v41
	s_waitcnt vmcnt(3)
	ds_write_b128 v129, v[106:109] offset:26624
	ds_write_b128 v130, v[110:113] offset:26752
	ds_write_b16 v131, v102 offset:18432
	ds_write_b16_d16_hi v131, v102 offset:18576
	v_fma_f32 v42, v42, s40, -v137
	v_fma_f32 v43, v43, s40, -v137
	v_fma_f32 v44, v44, s40, -v137
	v_fma_f32 v45, v45, s40, -v137
	s_waitcnt lgkmcnt(8)
	v_mfma_f32_32x32x16_bf16 v[138:153], v[186:189], v[94:97], v[138:153]
	v_exp_f32_e32 v42, v42
	v_exp_f32_e32 v43, v43
	v_exp_f32_e32 v44, v44
	v_exp_f32_e32 v45, v45
	v_fma_f32 v46, v46, s40, -v137
	v_fma_f32 v47, v47, s40, -v137
	v_fma_f32 v48, v48, s40, -v137
	v_mfma_f32_32x32x16_bf16 v[154:169], v[190:193], v[94:97], v[154:169]
	ds_read_b128 v[238:241], v136 offset:32
	ds_read_b128 v[242:245], v136 offset:4640
	v_fma_f32 v49, v49, s40, -v137
	v_exp_f32_e32 v46, v46
	v_exp_f32_e32 v47, v47
	v_exp_f32_e32 v48, v48
	v_exp_f32_e32 v49, v49
	v_add_f32_e32 v134, v134, v42
	v_add_f32_e32 v177, v177, v43
	s_waitcnt lgkmcnt(8)
	v_mfma_f32_32x32x16_bf16 v[138:153], v[194:197], v[98:101], v[138:153]
	v_add_f32_e32 v134, v134, v44
	v_add_f32_e32 v177, v177, v45
	v_add_f32_e32 v134, v134, v46
	v_add_f32_e32 v177, v177, v47
	v_add_f32_e32 v134, v134, v48
	v_add_f32_e32 v177, v177, v49
	v_cvt_pk_bf16_f32 v42, v42, v43
	v_mfma_f32_32x32x16_bf16 v[154:169], v[202:205], v[98:101], v[154:169]
	ds_read_b128 v[186:189], v136 offset:64
	ds_read_b128 v[190:193], v136 offset:4672
	v_cvt_pk_bf16_f32 v43, v44, v45
	v_cvt_pk_bf16_f32 v44, v46, v47
	v_cvt_pk_bf16_f32 v45, v48, v49
	ds_write_b16 v131, v103 offset:18720
	ds_write_b16_d16_hi v131, v103 offset:18864
	ds_write_b16 v131, v104 offset:19008
	ds_write_b16_d16_hi v131, v104 offset:19152
	v_fma_f32 v50, v50, s40, -v137
	v_fma_f32 v51, v51, s40, -v137
	v_fma_f32 v52, v52, s40, -v137
	v_fma_f32 v53, v53, s40, -v137
	s_waitcnt lgkmcnt(12)
	v_mfma_f32_32x32x16_bf16 v[18:33], v[210:213], v[34:37], v[18:33]
	v_exp_f32_e32 v50, v50
	v_exp_f32_e32 v51, v51
	v_exp_f32_e32 v52, v52
	v_exp_f32_e32 v53, v53
	v_fma_f32 v54, v54, s40, -v137
	v_fma_f32 v55, v55, s40, -v137
	v_fma_f32 v56, v56, s40, -v137
	v_mfma_f32_32x32x16_bf16 v[2:17], v[234:237], v[34:37], v[2:17]
	ds_read_b128 v[194:197], v136 offset:96
	ds_read_b128 v[202:205], v136 offset:4704
	v_fma_f32 v57, v57, s40, -v137
	v_exp_f32_e32 v54, v54
	v_exp_f32_e32 v55, v55
	v_exp_f32_e32 v56, v56
	v_exp_f32_e32 v57, v57
	v_add_f32_e32 v134, v134, v50
	v_add_f32_e32 v177, v177, v51
	s_waitcnt lgkmcnt(8)
	v_mfma_f32_32x32x16_bf16 v[18:33], v[238:241], v[42:45], v[18:33]
	v_add_f32_e32 v134, v134, v52
	v_add_f32_e32 v177, v177, v53
	v_add_f32_e32 v134, v134, v54
	v_add_f32_e32 v177, v177, v55
	v_add_f32_e32 v134, v134, v56
	v_add_f32_e32 v177, v177, v57
	v_cvt_pk_bf16_f32 v50, v50, v51
	v_mfma_f32_32x32x16_bf16 v[2:17], v[242:245], v[42:45], v[2:17]
	v_cvt_pk_bf16_f32 v51, v52, v53
	v_cvt_pk_bf16_f32 v52, v54, v55
	v_cvt_pk_bf16_f32 v53, v56, v57
	ds_write_b16 v131, v105 offset:19296
	ds_write_b16_d16_hi v131, v105 offset:19440
	v_fma_f32 v58, v58, s40, -v137
	v_fma_f32 v59, v59, s40, -v137
	v_fma_f32 v60, v60, s40, -v137
	v_fma_f32 v61, v61, s40, -v137
	v_exp_f32_e32 v58, v58
	v_exp_f32_e32 v59, v59
	v_exp_f32_e32 v60, v60
	v_exp_f32_e32 v61, v61
	s_waitcnt lgkmcnt(8)
	v_mfma_f32_32x32x16_bf16 v[18:33], v[186:189], v[50:53], v[18:33]
	v_fma_f32 v62, v62, s40, -v137
	v_fma_f32 v63, v63, s40, -v137
	v_fma_f32 v64, v64, s40, -v137
	v_fma_f32 v65, v65, s40, -v137
	v_exp_f32_e32 v62, v62
	v_exp_f32_e32 v63, v63
	v_exp_f32_e32 v64, v64
	v_exp_f32_e32 v65, v65
	v_add_f32_e32 v134, v134, v58
	v_add_f32_e32 v177, v177, v59
	v_add_f32_e32 v134, v134, v60
	v_add_f32_e32 v177, v177, v61
	v_add_f32_e32 v134, v134, v62
	v_add_f32_e32 v177, v177, v63
	v_mfma_f32_32x32x16_bf16 v[2:17], v[190:193], v[50:53], v[2:17]
	v_add_f32_e32 v134, v134, v64
	v_add_f32_e32 v177, v177, v65
	v_cvt_pk_bf16_f32 v58, v58, v59
	v_cvt_pk_bf16_f32 v59, v60, v61
	v_cvt_pk_bf16_f32 v60, v62, v63
	v_cvt_pk_bf16_f32 v61, v64, v65
	v_add_f32_e32 v134, v134, v177
	s_nop 0
	s_waitcnt lgkmcnt(2)
	v_mfma_f32_32x32x16_bf16 v[18:33], v[194:197], v[58:61], v[18:33]
	v_mfma_f32_32x32x16_bf16 v[2:17], v[202:205], v[58:61], v[2:17]
	s_branch .Lmla_nost0

; #define PG8_LAS __attribute__((address_space(3)))
;     DI bf16_t* kv() const { return (bf16_t*)(ws + WS_KV); }
; template <bool MLA> DI void tile_lstore(const TileRegs& R, lbf Ks, lbf Vt, int tid) {
;     constexpr int KLD = MLA ? 104 : 72;
;     const int key = tid >> 3, c = tid & 7;
;     *(PG8_LAS u32x4*)(Ks + key * KLD + 8 * c) = R.k;
;     if (MLA) { if (tid < 256) *(PG8_LAS u32x4*)(Ks + (tid >> 2) * KLD + 64 + 8 * (tid & 3)) = R.k2; }
;     { const int kv = tid & 63, cv = tid >> 6, kp = (kv & ~12) | ((kv & 4) << 1) | ((kv & 8) >> 1);
; #pragma unroll
;       for (int j = 0; j < 8; ++j) Vt[(8 * cv + j) * A_VLD + kp] = (bf16_t)(R.v[j >> 1] >> (16 * (j & 1))); }
; }
; template <bool PV> DI void online_step_mx(f32x16& x0, f32x16& x1, float mx, float& m, float& l, f32x16 (&O)[2]) {
;     const float mn = fmaxf(m, mx), alpha = __builtin_amdgcn_exp2f(m - mn);
;     float ls = 0.f;
; #pragma unroll
;     for (int i = 0; i < 16; ++i) { x0[i] = __builtin_amdgcn_exp2f(x0[i] - mn); x1[i] = __builtin_amdgcn_exp2f(x1[i] - mn); ls += x0[i] + x1[i]; }
;     ls += __shfl_xor(ls, 32);
;     l = l * alpha + ls; m = mn;
;     if (PV) { if (__any(alpha != 1.f)) {
; #pragma unroll
;         for (int i = 0; i < 16; ++i) { O[0][i] *= alpha; O[1][i] *= alpha; } } }
; }
.Lmla_rback_l0:
	v_fma_f32 v34, v34, s40, -v137
	v_fma_f32 v35, v35, s40, -v137
	v_fma_f32 v36, v36, s40, -v137
	v_fma_f32 v37, v37, s40, -v137
	v_exp_f32_e32 v34, v34
	v_exp_f32_e32 v35, v35
	v_exp_f32_e32 v36, v36
	v_exp_f32_e32 v37, v37
	v_fma_f32 v38, v38, s40, -v137
	v_fma_f32 v39, v39, s40, -v137
	v_fma_f32 v40, v40, s40, -v137
	v_fma_f32 v41, v41, s40, -v137
	v_exp_f32_e32 v38, v38
	v_exp_f32_e32 v39, v39
	v_exp_f32_e32 v40, v40
	v_exp_f32_e32 v41, v41
	v_add_f32_e32 v134, v134, v34
	v_add_f32_e32 v134, v134, v36
	v_add_f32_e32 v177, v35, v37
	v_add_f32_e32 v134, v134, v38
	v_add_f32_e32 v177, v177, v39
	v_add_f32_e32 v134, v134, v40
	v_add_f32_e32 v177, v177, v41
	v_cvt_pk_bf16_f32 v34, v34, v35
	v_cvt_pk_bf16_f32 v35, v36, v37
	v_cvt_pk_bf16_f32 v36, v38, v39
	v_cvt_pk_bf16_f32 v37, v40, v41
	s_waitcnt vmcnt(3)
	ds_write_b128 v129, v[106:109] offset:26624
	ds_write_b128 v130, v[110:113] offset:26752
	ds_write_b16 v131, v102 offset:18432
	ds_write_b16_d16_hi v131, v102 offset:18576
	v_fma_f32 v42, v42, s40, -v137
	v_fma_f32 v43, v43, s40, -v137
	v_fma_f32 v44, v44, s40, -v137
	v_fma_f32 v45, v45, s40, -v137
	v_exp_f32_e32 v42, v42
	v_exp_f32_e32 v43, v43
	v_exp_f32_e32 v44, v44
	v_exp_f32_e32 v45, v45
	s_waitcnt lgkmcnt(8)
	v_mfma_f32_32x32x16_bf16 v[18:33], v[186:189], v[34:37], v[18:33]
	v_fma_f32 v46, v46, s40, -v137
	v_fma_f32 v47, v47, s40, -v137
	v_fma_f32 v48, v48, s40, -v137
	v_fma_f32 v49, v49, s40, -v137
	v_exp_f32_e32 v46, v46
	v_exp_f32_e32 v47, v47
	v_exp_f32_e32 v48, v48
	v_exp_f32_e32 v49, v49
	v_add_f32_e32 v134, v134, v42
	v_add_f32_e32 v177, v177, v43
	v_add_f32_e32 v134, v134, v44
	v_add_f32_e32 v177, v177, v45
	v_add_f32_e32 v134, v134, v46
	v_add_f32_e32 v177, v177, v47
	v_mfma_f32_32x32x16_bf16 v[2:17], v[190:193], v[34:37], v[2:17]
	ds_read_b128 v[238:241], v136 offset:96
	ds_read_b128 v[242:245], v136 offset:4704
	v_add_f32_e32 v134, v134, v48
	v_add_f32_e32 v177, v177, v49
	v_cvt_pk_bf16_f32 v42, v42, v43
	v_cvt_pk_bf16_f32 v43, v44, v45
	v_cvt_pk_bf16_f32 v44, v46, v47
	v_cvt_pk_bf16_f32 v45, v48, v49
	ds_write_b16 v131, v103 offset:18720
	ds_write_b16_d16_hi v131, v103 offset:18864
	ds_write_b16 v131, v104 offset:19008
	ds_write_b16_d16_hi v131, v104 offset:19152
	v_fma_f32 v50, v50, s40, -v137
	v_fma_f32 v51, v51, s40, -v137
	v_fma_f32 v52, v52, s40, -v137
	v_fma_f32 v53, v53, s40, -v137
	v_exp_f32_e32 v50, v50
	v_exp_f32_e32 v51, v51
	v_exp_f32_e32 v52, v52
	v_exp_f32_e32 v53, v53
	s_waitcnt lgkmcnt(12)
	v_mfma_f32_32x32x16_bf16 v[18:33], v[194:197], v[42:45], v[18:33]
	v_fma_f32 v54, v54, s40, -v137
	v_fma_f32 v55, v55, s40, -v137
	v_fma_f32 v56, v56, s40, -v137
	v_fma_f32 v57, v57, s40, -v137
	v_exp_f32_e32 v54, v54
	v_exp_f32_e32 v55, v55
	v_exp_f32_e32 v56, v56
	v_exp_f32_e32 v57, v57
	v_add_f32_e32 v134, v134, v50
	v_add_f32_e32 v177, v177, v51
	v_add_f32_e32 v134, v134, v52
	v_add_f32_e32 v177, v177, v53
	v_add_f32_e32 v134, v134, v54
	v_add_f32_e32 v177, v177, v55
	v_mfma_f32_32x32x16_bf16 v[2:17], v[202:205], v[42:45], v[2:17]
	v_add_f32_e32 v134, v134, v56
	v_add_f32_e32 v177, v177, v57
	v_cvt_pk_bf16_f32 v50, v50, v51
	v_cvt_pk_bf16_f32 v51, v52, v53
	v_cvt_pk_bf16_f32 v52, v54, v55
	v_cvt_pk_bf16_f32 v53, v56, v57
	ds_write_b16 v131, v105 offset:19296
	ds_write_b16_d16_hi v131, v105 offset:19440
	v_fma_f32 v58, v58, s40, -v137
	v_fma_f32 v59, v59, s40, -v137
	v_fma_f32 v60, v60, s40, -v137
	v_fma_f32 v61, v61, s40, -v137
	v_exp_f32_e32 v58, v58
	v_exp_f32_e32 v59, v59
	v_exp_f32_e32 v60, v60
	v_exp_f32_e32 v61, v61
	s_waitcnt lgkmcnt(12)
	v_mfma_f32_32x32x16_bf16 v[18:33], v[210:213], v[50:53], v[18:33]
	v_fma_f32 v62, v62, s40, -v137
	v_fma_f32 v63, v63, s40, -v137
	v_fma_f32 v64, v64, s40, -v137
	v_fma_f32 v65, v65, s40, -v137
	v_exp_f32_e32 v62, v62
	v_exp_f32_e32 v63, v63
	v_exp_f32_e32 v64, v64
	v_exp_f32_e32 v65, v65
	v_add_f32_e32 v134, v134, v58
	v_add_f32_e32 v177, v177, v59
	v_add_f32_e32 v134, v134, v60
	v_add_f32_e32 v177, v177, v61
	v_add_f32_e32 v134, v134, v62
	v_add_f32_e32 v177, v177, v63
	v_mfma_f32_32x32x16_bf16 v[2:17], v[234:237], v[50:53], v[2:17]
	v_add_f32_e32 v134, v134, v64
	v_add_f32_e32 v177, v177, v65
	v_cvt_pk_bf16_f32 v58, v58, v59
	v_cvt_pk_bf16_f32 v59, v60, v61
	v_cvt_pk_bf16_f32 v60, v62, v63
	v_cvt_pk_bf16_f32 v61, v64, v65
	v_add_f32_e32 v134, v134, v177
	s_nop 0
	s_waitcnt lgkmcnt(6)
	v_mfma_f32_32x32x16_bf16 v[18:33], v[238:241], v[58:61], v[18:33]
	v_mfma_f32_32x32x16_bf16 v[2:17], v[242:245], v[58:61], v[2:17]
	s_branch .Lmla_nost0
.Lmla_coop0:
	s_waitcnt vmcnt(3)
	s_add_i32 s24, s17, 2
	s_cmp_lt_i32 s24, s16
	s_cbranch_scc0 .Lmla_nost0
	ds_write_b128 v129, v[106:109] offset:26624
	ds_write_b128 v130, v[110:113] offset:26752
	ds_write_b16 v131, v102 offset:18432
	ds_write_b16_d16_hi v131, v102 offset:18576
	ds_write_b16 v131, v103 offset:18720
	ds_write_b16_d16_hi v131, v103 offset:18864
	ds_write_b16 v131, v104 offset:19008
	ds_write_b16_d16_hi v131, v104 offset:19152
	ds_write_b16 v131, v105 offset:19296
	ds_write_b16_d16_hi v131, v105 offset:19440

; #define PG8_LAS __attribute__((address_space(3)))
;     DI bf16_t* kv() const { return (bf16_t*)(ws + WS_KV); }
; template <bool MLA> DI void tile_lstore(const TileRegs& R, lbf Ks, lbf Vt, int tid) {
;     constexpr int KLD = MLA ? 104 : 72;
;     const int key = tid >> 3, c = tid & 7;
;     *(PG8_LAS u32x4*)(Ks + key * KLD + 8 * c) = R.k;
;     if (MLA) { if (tid < 256) *(PG8_LAS u32x4*)(Ks + (tid >> 2) * KLD + 64 + 8 * (tid & 3)) = R.k2; }
;     { const int kv = tid & 63, cv = tid >> 6, kp = (kv & ~12) | ((kv & 4) << 1) | ((kv & 8) >> 1);
; #pragma unroll
;       for (int j = 0; j < 8; ++j) Vt[(8 * cv + j) * A_VLD + kp] = (bf16_t)(R.v[j >> 1] >> (16 * (j & 1))); }
; }
; template <bool PV> DI void online_step_mx(f32x16& x0, f32x16& x1, float mx, float& m, float& l, f32x16 (&O)[2]) {
;     const float mn = fmaxf(m, mx), alpha = __builtin_amdgcn_exp2f(m - mn);
;     float ls = 0.f;
; #pragma unroll
;     for (int i = 0; i < 16; ++i) { x0[i] = __builtin_amdgcn_exp2f(x0[i] - mn); x1[i] = __builtin_amdgcn_exp2f(x1[i] - mn); ls += x0[i] + x1[i]; }
;     ls += __shfl_xor(ls, 32);
;     l = l * alpha + ls; m = mn;
;     if (PV) { if (__any(alpha != 1.f)) {
; #pragma unroll
;         for (int i = 0; i < 16; ++i) { O[0][i] *= alpha; O[1][i] *= alpha; } } }
; }
.Lmla_rback_f1:
	v_fma_f32 v138, v138, s40, -v137
	v_fma_f32 v139, v139, s40, -v137
	v_fma_f32 v140, v140, s40, -v137
	v_fma_f32 v141, v141, s40, -v137
	s_waitcnt lgkmcnt(4)
	v_mfma_f32_32x32x16_bf16 v[34:49], v[210:213], v[74:77], v[34:49]
	v_exp_f32_e32 v138, v138
	v_exp_f32_e32 v139, v139
	v_exp_f32_e32 v140, v140
	v_exp_f32_e32 v141, v141
	v_fma_f32 v142, v142, s40, -v137
	v_fma_f32 v143, v143, s40, -v137
	v_fma_f32 v144, v144, s40, -v137
	v_mfma_f32_32x32x16_bf16 v[50:65], v[234:237], v[74:77], v[50:65]
	ds_read_b128 v[194:197], v135 offset:26784
	ds_read_b128 v[202:205], v135 offset:33440
	v_fma_f32 v145, v145, s40, -v137
	v_exp_f32_e32 v142, v142
	v_exp_f32_e32 v143, v143
	v_exp_f32_e32 v144, v144
	v_exp_f32_e32 v145, v145
	v_add_f32_e32 v134, v134, v138
	s_waitcnt lgkmcnt(4)
	v_mfma_f32_32x32x16_bf16 v[34:49], v[238:241], v[78:81], v[34:49]
	v_add_f32_e32 v134, v134, v140
	v_add_f32_e32 v177, v139, v141
	v_add_f32_e32 v134, v134, v142
	v_add_f32_e32 v177, v177, v143
	v_add_f32_e32 v134, v134, v144
	v_add_f32_e32 v177, v177, v145
	v_cvt_pk_bf16_f32 v138, v138, v139
	v_mfma_f32_32x32x16_bf16 v[50:65], v[242:245], v[78:81], v[50:65]
	ds_read_b128 v[210:213], v136 offset:9216
	ds_read_b128 v[234:237], v136 offset:13824
	v_cvt_pk_bf16_f32 v139, v140, v141
	v_cvt_pk_bf16_f32 v140, v142, v143
	v_cvt_pk_bf16_f32 v141, v144, v145
	s_waitcnt vmcnt(3)
	ds_write_b128 v129, v[86:89] offset:39936
	ds_write_b128 v130, v[90:93] offset:40064
	ds_write_b16 v131, v82 offset:27648
	ds_write_b16_d16_hi v131, v82 offset:27792
	v_fma_f32 v146, v146, s40, -v137
	v_fma_f32 v147, v147, s40, -v137
	v_fma_f32 v148, v148, s40, -v137
	v_fma_f32 v149, v149, s40, -v137
	s_waitcnt lgkmcnt(8)
	v_mfma_f32_32x32x16_bf16 v[34:49], v[186:189], v[94:97], v[34:49]
	v_exp_f32_e32 v146, v146
	v_exp_f32_e32 v147, v147
	v_exp_f32_e32 v148, v148
	v_exp_f32_e32 v149, v149
	v_fma_f32 v150, v150, s40, -v137
	v_fma_f32 v151, v151, s40, -v137
	v_fma_f32 v152, v152, s40, -v137
	v_mfma_f32_32x32x16_bf16 v[50:65], v[190:193], v[94:97], v[50:65]
	ds_read_b128 v[238:241], v136 offset:9248
	ds_read_b128 v[242:245], v136 offset:13856
	v_fma_f32 v153, v153, s40, -v137
	v_exp_f32_e32 v150, v150
	v_exp_f32_e32 v151, v151
	v_exp_f32_e32 v152, v152
	v_exp_f32_e32 v153, v153
	v_add_f32_e32 v134, v134, v146
	v_add_f32_e32 v177, v177, v147
	s_waitcnt lgkmcnt(8)
	v_mfma_f32_32x32x16_bf16 v[34:49], v[194:197], v[98:101], v[34:49]
	v_add_f32_e32 v134, v134, v148
	v_add_f32_e32 v177, v177, v149
	v_add_f32_e32 v134, v134, v150
	v_add_f32_e32 v177, v177, v151
	v_add_f32_e32 v134, v134, v152
	v_add_f32_e32 v177, v177, v153
	v_cvt_pk_bf16_f32 v146, v146, v147
	v_mfma_f32_32x32x16_bf16 v[50:65], v[202:205], v[98:101], v[50:65]
	ds_read_b128 v[186:189], v136 offset:9280
	ds_read_b128 v[190:193], v136 offset:13888
	v_cvt_pk_bf16_f32 v147, v148, v149
	v_cvt_pk_bf16_f32 v148, v150, v151
	v_cvt_pk_bf16_f32 v149, v152, v153
	ds_write_b16 v131, v83 offset:27936
	ds_write_b16_d16_hi v131, v83 offset:28080
	ds_write_b16 v131, v84 offset:28224
	ds_write_b16_d16_hi v131, v84 offset:28368
	v_fma_f32 v154, v154, s40, -v137
	v_fma_f32 v155, v155, s40, -v137
	v_fma_f32 v156, v156, s40, -v137
	v_fma_f32 v157, v157, s40, -v137
	s_waitcnt lgkmcnt(12)
	v_mfma_f32_32x32x16_bf16 v[18:33], v[210:213], v[138:141], v[18:33]
	v_exp_f32_e32 v154, v154
	v_exp_f32_e32 v155, v155
	v_exp_f32_e32 v156, v156
	v_exp_f32_e32 v157, v157
	v_fma_f32 v158, v158, s40, -v137
	v_fma_f32 v159, v159, s40, -v137
	v_fma_f32 v160, v160, s40, -v137
	v_mfma_f32_32x32x16_bf16 v[2:17], v[234:237], v[138:141], v[2:17]
	ds_read_b128 v[194:197], v136 offset:9312
	ds_read_b128 v[202:205], v136 offset:13920
	v_fma_f32 v161, v161, s40, -v137
	v_exp_f32_e32 v158, v158
	v_exp_f32_e32 v159, v159
	v_exp_f32_e32 v160, v160
	v_exp_f32_e32 v161, v161
	v_add_f32_e32 v134, v134, v154
	v_add_f32_e32 v177, v177, v155
	s_waitcnt lgkmcnt(8)
	v_mfma_f32_32x32x16_bf16 v[18:33], v[238:241], v[146:149], v[18:33]
	v_add_f32_e32 v134, v134, v156
	v_add_f32_e32 v177, v177, v157
	v_add_f32_e32 v134, v134, v158
	v_add_f32_e32 v177, v177, v159
	v_add_f32_e32 v134, v134, v160
	v_add_f32_e32 v177, v177, v161
	v_cvt_pk_bf16_f32 v154, v154, v155
	v_mfma_f32_32x32x16_bf16 v[2:17], v[242:245], v[146:149], v[2:17]
	v_cvt_pk_bf16_f32 v155, v156, v157
	v_cvt_pk_bf16_f32 v156, v158, v159
	v_cvt_pk_bf16_f32 v157, v160, v161
	ds_write_b16 v131, v85 offset:28512
	ds_write_b16_d16_hi v131, v85 offset:28656
	v_fma_f32 v162, v162, s40, -v137
	v_fma_f32 v163, v163, s40, -v137
	v_fma_f32 v164, v164, s40, -v137
	v_fma_f32 v165, v165, s40, -v137
	v_exp_f32_e32 v162, v162
	v_exp_f32_e32 v163, v163
	v_exp_f32_e32 v164, v164
	v_exp_f32_e32 v165, v165
	s_waitcnt lgkmcnt(8)
	v_mfma_f32_32x32x16_bf16 v[18:33], v[186:189], v[154:157], v[18:33]
	v_fma_f32 v166, v166, s40, -v137
	v_fma_f32 v167, v167, s40, -v137
	v_fma_f32 v168, v168, s40, -v137
	v_fma_f32 v169, v169, s40, -v137
	v_exp_f32_e32 v166, v166
	v_exp_f32_e32 v167, v167
	v_exp_f32_e32 v168, v168
	v_exp_f32_e32 v169, v169
	v_add_f32_e32 v134, v134, v162
	v_add_f32_e32 v177, v177, v163
	v_add_f32_e32 v134, v134, v164
	v_add_f32_e32 v177, v177, v165
	v_add_f32_e32 v134, v134, v166
	v_add_f32_e32 v177, v177, v167
	v_mfma_f32_32x32x16_bf16 v[2:17], v[190:193], v[154:157], v[2:17]
	v_add_f32_e32 v134, v134, v168
	v_add_f32_e32 v177, v177, v169
	v_cvt_pk_bf16_f32 v162, v162, v163
	v_cvt_pk_bf16_f32 v163, v164, v165
	v_cvt_pk_bf16_f32 v164, v166, v167
	v_cvt_pk_bf16_f32 v165, v168, v169
	v_add_f32_e32 v134, v134, v177
	s_nop 0
	s_waitcnt lgkmcnt(2)
	v_mfma_f32_32x32x16_bf16 v[18:33], v[194:197], v[162:165], v[18:33]
	v_mfma_f32_32x32x16_bf16 v[2:17], v[202:205], v[162:165], v[2:17]
	s_branch .Lmla_nost1

; #define PG8_LAS __attribute__((address_space(3)))
;     DI bf16_t* kv() const { return (bf16_t*)(ws + WS_KV); }
; template <bool MLA> DI void tile_lstore(const TileRegs& R, lbf Ks, lbf Vt, int tid) {
;     constexpr int KLD = MLA ? 104 : 72;
;     const int key = tid >> 3, c = tid & 7;
;     *(PG8_LAS u32x4*)(Ks + key * KLD + 8 * c) = R.k;
;     if (MLA) { if (tid < 256) *(PG8_LAS u32x4*)(Ks + (tid >> 2) * KLD + 64 + 8 * (tid & 3)) = R.k2; }
;     { const int kv = tid & 63, cv = tid >> 6, kp = (kv & ~12) | ((kv & 4) << 1) | ((kv & 8) >> 1);
; #pragma unroll
;       for (int j = 0; j < 8; ++j) Vt[(8 * cv + j) * A_VLD + kp] = (bf16_t)(R.v[j >> 1] >> (16 * (j & 1))); }
; }
; template <bool PV> DI void online_step_mx(f32x16& x0, f32x16& x1, float mx, float& m, float& l, f32x16 (&O)[2]) {
;     const float mn = fmaxf(m, mx), alpha = __builtin_amdgcn_exp2f(m - mn);
;     float ls = 0.f;
; #pragma unroll
;     for (int i = 0; i < 16; ++i) { x0[i] = __builtin_amdgcn_exp2f(x0[i] - mn); x1[i] = __builtin_amdgcn_exp2f(x1[i] - mn); ls += x0[i] + x1[i]; }
;     ls += __shfl_xor(ls, 32);
;     l = l * alpha + ls; m = mn;
;     if (PV) { if (__any(alpha != 1.f)) {
; #pragma unroll
;         for (int i = 0; i < 16; ++i) { O[0][i] *= alpha; O[1][i] *= alpha; } } }
; }
.Lmla_rback_l1:
	v_fma_f32 v138, v138, s40, -v137
	v_fma_f32 v139, v139, s40, -v137
	v_fma_f32 v140, v140, s40, -v137
	v_fma_f32 v141, v141, s40, -v137
	v_exp_f32_e32 v138, v138
	v_exp_f32_e32 v139, v139
	v_exp_f32_e32 v140, v140
	v_exp_f32_e32 v141, v141
	v_fma_f32 v142, v142, s40, -v137
	v_fma_f32 v143, v143, s40, -v137
	v_fma_f32 v144, v144, s40, -v137
	v_fma_f32 v145, v145, s40, -v137
	v_exp_f32_e32 v142, v142
	v_exp_f32_e32 v143, v143
	v_exp_f32_e32 v144, v144
	v_exp_f32_e32 v145, v145
	v_add_f32_e32 v134, v134, v138
	v_add_f32_e32 v134, v134, v140
	v_add_f32_e32 v177, v139, v141
	v_add_f32_e32 v134, v134, v142
	v_add_f32_e32 v177, v177, v143
	v_add_f32_e32 v134, v134, v144
	v_add_f32_e32 v177, v177, v145
	v_cvt_pk_bf16_f32 v138, v138, v139
	v_cvt_pk_bf16_f32 v139, v140, v141
	v_cvt_pk_bf16_f32 v140, v142, v143
	v_cvt_pk_bf16_f32 v141, v144, v145
	s_waitcnt vmcnt(3)
	ds_write_b128 v129, v[86:89] offset:39936
	ds_write_b128 v130, v[90:93] offset:40064
	ds_write_b16 v131, v82 offset:27648
	ds_write_b16_d16_hi v131, v82 offset:27792
	v_fma_f32 v146, v146, s40, -v137
	v_fma_f32 v147, v147, s40, -v137
	v_fma_f32 v148, v148, s40, -v137
	v_fma_f32 v149, v149, s40, -v137
	v_exp_f32_e32 v146, v146
	v_exp_f32_e32 v147, v147
	v_exp_f32_e32 v148, v148
	v_exp_f32_e32 v149, v149
	s_waitcnt lgkmcnt(8)
	v_mfma_f32_32x32x16_bf16 v[18:33], v[186:189], v[138:141], v[18:33]
	v_fma_f32 v150, v150, s40, -v137
	v_fma_f32 v151, v151, s40, -v137
	v_fma_f32 v152, v152, s40, -v137
	v_fma_f32 v153, v153, s40, -v137
	v_exp_f32_e32 v150, v150
	v_exp_f32_e32 v151, v151
	v_exp_f32_e32 v152, v152
	v_exp_f32_e32 v153, v153
	v_add_f32_e32 v134, v134, v146
	v_add_f32_e32 v177, v177, v147
	v_add_f32_e32 v134, v134, v148
	v_add_f32_e32 v177, v177, v149
	v_add_f32_e32 v134, v134, v150
	v_add_f32_e32 v177, v177, v151
	v_mfma_f32_32x32x16_bf16 v[2:17], v[190:193], v[138:141], v[2:17]
	ds_read_b128 v[238:241], v136 offset:9312
	ds_read_b128 v[242:245], v136 offset:13920
	v_add_f32_e32 v134, v134, v152
	v_add_f32_e32 v177, v177, v153
	v_cvt_pk_bf16_f32 v146, v146, v147
	v_cvt_pk_bf16_f32 v147, v148, v149
	v_cvt_pk_bf16_f32 v148, v150, v151
	v_cvt_pk_bf16_f32 v149, v152, v153
	ds_write_b16 v131, v83 offset:27936
	ds_write_b16_d16_hi v131, v83 offset:28080
	ds_write_b16 v131, v84 offset:28224
	ds_write_b16_d16_hi v131, v84 offset:28368
	v_fma_f32 v154, v154, s40, -v137
	v_fma_f32 v155, v155, s40, -v137
	v_fma_f32 v156, v156, s40, -v137
	v_fma_f32 v157, v157, s40, -v137
	v_exp_f32_e32 v154, v154
	v_exp_f32_e32 v155, v155
	v_exp_f32_e32 v156, v156
	v_exp_f32_e32 v157, v157
	s_waitcnt lgkmcnt(12)
	v_mfma_f32_32x32x16_bf16 v[18:33], v[194:197], v[146:149], v[18:33]
	v_fma_f32 v158, v158, s40, -v137
	v_fma_f32 v159, v159, s40, -v137
	v_fma_f32 v160, v160, s40, -v137
	v_fma_f32 v161, v161, s40, -v137
	v_exp_f32_e32 v158, v158
	v_exp_f32_e32 v159, v159
	v_exp_f32_e32 v160, v160
	v_exp_f32_e32 v161, v161
	v_add_f32_e32 v134, v134, v154
	v_add_f32_e32 v177, v177, v155
	v_add_f32_e32 v134, v134, v156
	v_add_f32_e32 v177, v177, v157
	v_add_f32_e32 v134, v134, v158
	v_add_f32_e32 v177, v177, v159
	v_mfma_f32_32x32x16_bf16 v[2:17], v[202:205], v[146:149], v[2:17]
	v_add_f32_e32 v134, v134, v160
	v_add_f32_e32 v177, v177, v161
	v_cvt_pk_bf16_f32 v154, v154, v155
	v_cvt_pk_bf16_f32 v155, v156, v157
	v_cvt_pk_bf16_f32 v156, v158, v159
	v_cvt_pk_bf16_f32 v157, v160, v161
	ds_write_b16 v131, v85 offset:28512
	ds_write_b16_d16_hi v131, v85 offset:28656
	v_fma_f32 v162, v162, s40, -v137
	v_fma_f32 v163, v163, s40, -v137
	v_fma_f32 v164, v164, s40, -v137
	v_fma_f32 v165, v165, s40, -v137
	v_exp_f32_e32 v162, v162
	v_exp_f32_e32 v163, v163
	v_exp_f32_e32 v164, v164
	v_exp_f32_e32 v165, v165
	s_waitcnt lgkmcnt(12)
	v_mfma_f32_32x32x16_bf16 v[18:33], v[210:213], v[154:157], v[18:33]
	v_fma_f32 v166, v166, s40, -v137
	v_fma_f32 v167, v167, s40, -v137
	v_fma_f32 v168, v168, s40, -v137
	v_fma_f32 v169, v169, s40, -v137
	v_exp_f32_e32 v166, v166
	v_exp_f32_e32 v167, v167
	v_exp_f32_e32 v168, v168
	v_exp_f32_e32 v169, v169
	v_add_f32_e32 v134, v134, v162
	v_add_f32_e32 v177, v177, v163
	v_add_f32_e32 v134, v134, v164
	v_add_f32_e32 v177, v177, v165
	v_add_f32_e32 v134, v134, v166
	v_add_f32_e32 v177, v177, v167
	v_mfma_f32_32x32x16_bf16 v[2:17], v[234:237], v[154:157], v[2:17]
	v_add_f32_e32 v134, v134, v168
	v_add_f32_e32 v177, v177, v169
	v_cvt_pk_bf16_f32 v162, v162, v163
	v_cvt_pk_bf16_f32 v163, v164, v165
	v_cvt_pk_bf16_f32 v164, v166, v167
	v_cvt_pk_bf16_f32 v165, v168, v169
	v_add_f32_e32 v134, v134, v177
	s_nop 0
	s_waitcnt lgkmcnt(6)
	v_mfma_f32_32x32x16_bf16 v[18:33], v[238:241], v[162:165], v[18:33]
	v_mfma_f32_32x32x16_bf16 v[2:17], v[242:245], v[162:165], v[2:17]
	s_branch .Lmla_nost1
.Lmla_coop1:
	s_waitcnt vmcnt(3)
	s_add_i32 s24, s17, 2
	s_cmp_lt_i32 s24, s16
	s_cbranch_scc0 .Lmla_nost1
	ds_write_b128 v129, v[86:89] offset:39936
	ds_write_b128 v130, v[90:93] offset:40064
	ds_write_b16 v131, v82 offset:27648
	ds_write_b16_d16_hi v131, v82 offset:27792
	ds_write_b16 v131, v83 offset:27936
	ds_write_b16_d16_hi v131, v83 offset:28080
	ds_write_b16 v131, v84 offset:28224
	ds_write_b16_d16_hi v131, v84 offset:28368
	ds_write_b16 v131, v85 offset:28512
	ds_write_b16_d16_hi v131, v85 offset:28656

; #define PG8_LAS __attribute__((address_space(3)))
;     DI bf16_t* kv() const { return (bf16_t*)(ws + WS_KV); }
; template <bool MLA> DI void tile_lstore(const TileRegs& R, lbf Ks, lbf Vt, int tid) {
;     constexpr int KLD = MLA ? 104 : 72;
;     const int key = tid >> 3, c = tid & 7;
;     *(PG8_LAS u32x4*)(Ks + key * KLD + 8 * c) = R.k;
;     if (MLA) { if (tid < 256) *(PG8_LAS u32x4*)(Ks + (tid >> 2) * KLD + 64 + 8 * (tid & 3)) = R.k2; }
;     { const int kv = tid & 63, cv = tid >> 6, kp = (kv & ~12) | ((kv & 4) << 1) | ((kv & 8) >> 1);
; #pragma unroll
;       for (int j = 0; j < 8; ++j) Vt[(8 * cv + j) * A_VLD + kp] = (bf16_t)(R.v[j >> 1] >> (16 * (j & 1))); }
; }
; template <bool PV> DI void online_step_mx(f32x16& x0, f32x16& x1, float mx, float& m, float& l, f32x16 (&O)[2]) {
;     const float mn = fmaxf(m, mx), alpha = __builtin_amdgcn_exp2f(m - mn);
;     float ls = 0.f;
; #pragma unroll
;     for (int i = 0; i < 16; ++i) { x0[i] = __builtin_amdgcn_exp2f(x0[i] - mn); x1[i] = __builtin_amdgcn_exp2f(x1[i] - mn); ls += x0[i] + x1[i]; }
;     ls += __shfl_xor(ls, 32);
;     l = l * alpha + ls; m = mn;
;     if (PV) { if (__any(alpha != 1.f)) {
; #pragma unroll
;         for (int i = 0; i < 16; ++i) { O[0][i] *= alpha; O[1][i] *= alpha; } } }
; }
.Lmla_rback_f2:
	v_fma_f32 v34, v34, s40, -v137
	v_fma_f32 v35, v35, s40, -v137
	v_fma_f32 v36, v36, s40, -v137
	v_fma_f32 v37, v37, s40, -v137
	s_waitcnt lgkmcnt(4)
	v_mfma_f32_32x32x16_bf16 v[138:153], v[210:213], v[74:77], v[138:153]
	v_exp_f32_e32 v34, v34
	v_exp_f32_e32 v35, v35
	v_exp_f32_e32 v36, v36
	v_exp_f32_e32 v37, v37
	v_fma_f32 v38, v38, s40, -v137
	v_fma_f32 v39, v39, s40, -v137
	v_fma_f32 v40, v40, s40, -v137
	v_mfma_f32_32x32x16_bf16 v[154:169], v[234:237], v[74:77], v[154:169]
	ds_read_b128 v[194:197], v135 offset:40096
	ds_read_b128 v[202:205], v135 offset:46752
	v_fma_f32 v41, v41, s40, -v137
	v_exp_f32_e32 v38, v38
	v_exp_f32_e32 v39, v39
	v_exp_f32_e32 v40, v40
	v_exp_f32_e32 v41, v41
	v_add_f32_e32 v134, v134, v34
	s_waitcnt lgkmcnt(4)
	v_mfma_f32_32x32x16_bf16 v[138:153], v[238:241], v[78:81], v[138:153]
	v_add_f32_e32 v134, v134, v36
	v_add_f32_e32 v177, v35, v37
	v_add_f32_e32 v134, v134, v38
	v_add_f32_e32 v177, v177, v39
	v_add_f32_e32 v134, v134, v40
	v_add_f32_e32 v177, v177, v41
	v_cvt_pk_bf16_f32 v34, v34, v35
	v_mfma_f32_32x32x16_bf16 v[154:169], v[242:245], v[78:81], v[154:169]
	ds_read_b128 v[210:213], v136 offset:18432
	ds_read_b128 v[234:237], v136 offset:23040
	v_cvt_pk_bf16_f32 v35, v36, v37
	v_cvt_pk_bf16_f32 v36, v38, v39
	v_cvt_pk_bf16_f32 v37, v40, v41
	s_waitcnt vmcnt(3)
	ds_write_b128 v129, v[106:109] offset:0
	ds_write_b128 v130, v[110:113] offset:128
	ds_write_b16 v131, v102 offset:0
	ds_write_b16_d16_hi v131, v102 offset:144
	v_fma_f32 v42, v42, s40, -v137
	v_fma_f32 v43, v43, s40, -v137
	v_fma_f32 v44, v44, s40, -v137
	v_fma_f32 v45, v45, s40, -v137
	s_waitcnt lgkmcnt(8)
	v_mfma_f32_32x32x16_bf16 v[138:153], v[186:189], v[94:97], v[138:153]
	v_exp_f32_e32 v42, v42
	v_exp_f32_e32 v43, v43
	v_exp_f32_e32 v44, v44
	v_exp_f32_e32 v45, v45
	v_fma_f32 v46, v46, s40, -v137
	v_fma_f32 v47, v47, s40, -v137
	v_fma_f32 v48, v48, s40, -v137
	v_mfma_f32_32x32x16_bf16 v[154:169], v[190:193], v[94:97], v[154:169]
	ds_read_b128 v[238:241], v136 offset:18464
	ds_read_b128 v[242:245], v136 offset:23072
	v_fma_f32 v49, v49, s40, -v137
	v_exp_f32_e32 v46, v46
	v_exp_f32_e32 v47, v47
	v_exp_f32_e32 v48, v48
	v_exp_f32_e32 v49, v49
	v_add_f32_e32 v134, v134, v42
	v_add_f32_e32 v177, v177, v43
	s_waitcnt lgkmcnt(8)
	v_mfma_f32_32x32x16_bf16 v[138:153], v[194:197], v[98:101], v[138:153]
	v_add_f32_e32 v134, v134, v44
	v_add_f32_e32 v177, v177, v45
	v_add_f32_e32 v134, v134, v46
	v_add_f32_e32 v177, v177, v47
	v_add_f32_e32 v134, v134, v48
	v_add_f32_e32 v177, v177, v49
	v_cvt_pk_bf16_f32 v42, v42, v43
	v_mfma_f32_32x32x16_bf16 v[154:169], v[202:205], v[98:101], v[154:169]
	ds_read_b128 v[186:189], v136 offset:18496
	ds_read_b128 v[190:193], v136 offset:23104
	v_cvt_pk_bf16_f32 v43, v44, v45
	v_cvt_pk_bf16_f32 v44, v46, v47
	v_cvt_pk_bf16_f32 v45, v48, v49
	ds_write_b16 v131, v103 offset:288
	ds_write_b16_d16_hi v131, v103 offset:432
	ds_write_b16 v131, v104 offset:576
	ds_write_b16_d16_hi v131, v104 offset:720
	v_fma_f32 v50, v50, s40, -v137
	v_fma_f32 v51, v51, s40, -v137
	v_fma_f32 v52, v52, s40, -v137
	v_fma_f32 v53, v53, s40, -v137
	s_waitcnt lgkmcnt(12)
	v_mfma_f32_32x32x16_bf16 v[18:33], v[210:213], v[34:37], v[18:33]
	v_exp_f32_e32 v50, v50
	v_exp_f32_e32 v51, v51
	v_exp_f32_e32 v52, v52
	v_exp_f32_e32 v53, v53
	v_fma_f32 v54, v54, s40, -v137
	v_fma_f32 v55, v55, s40, -v137
	v_fma_f32 v56, v56, s40, -v137
	v_mfma_f32_32x32x16_bf16 v[2:17], v[234:237], v[34:37], v[2:17]
	ds_read_b128 v[194:197], v136 offset:18528
	ds_read_b128 v[202:205], v136 offset:23136
	v_fma_f32 v57, v57, s40, -v137
	v_exp_f32_e32 v54, v54
	v_exp_f32_e32 v55, v55
	v_exp_f32_e32 v56, v56
	v_exp_f32_e32 v57, v57
	v_add_f32_e32 v134, v134, v50
	v_add_f32_e32 v177, v177, v51
	s_waitcnt lgkmcnt(8)
	v_mfma_f32_32x32x16_bf16 v[18:33], v[238:241], v[42:45], v[18:33]
	v_add_f32_e32 v134, v134, v52
	v_add_f32_e32 v177, v177, v53
	v_add_f32_e32 v134, v134, v54
	v_add_f32_e32 v177, v177, v55
	v_add_f32_e32 v134, v134, v56
	v_add_f32_e32 v177, v177, v57
	v_cvt_pk_bf16_f32 v50, v50, v51
	v_mfma_f32_32x32x16_bf16 v[2:17], v[242:245], v[42:45], v[2:17]
	v_cvt_pk_bf16_f32 v51, v52, v53
	v_cvt_pk_bf16_f32 v52, v54, v55
	v_cvt_pk_bf16_f32 v53, v56, v57
	ds_write_b16 v131, v105 offset:864
	ds_write_b16_d16_hi v131, v105 offset:1008
	v_fma_f32 v58, v58, s40, -v137
	v_fma_f32 v59, v59, s40, -v137
	v_fma_f32 v60, v60, s40, -v137
	v_fma_f32 v61, v61, s40, -v137
	v_exp_f32_e32 v58, v58
	v_exp_f32_e32 v59, v59
	v_exp_f32_e32 v60, v60
	v_exp_f32_e32 v61, v61
	s_waitcnt lgkmcnt(8)
	v_mfma_f32_32x32x16_bf16 v[18:33], v[186:189], v[50:53], v[18:33]
	v_fma_f32 v62, v62, s40, -v137
	v_fma_f32 v63, v63, s40, -v137
	v_fma_f32 v64, v64, s40, -v137
	v_fma_f32 v65, v65, s40, -v137
	v_exp_f32_e32 v62, v62
	v_exp_f32_e32 v63, v63
	v_exp_f32_e32 v64, v64
	v_exp_f32_e32 v65, v65
	v_add_f32_e32 v134, v134, v58
	v_add_f32_e32 v177, v177, v59
	v_add_f32_e32 v134, v134, v60
	v_add_f32_e32 v177, v177, v61
	v_add_f32_e32 v134, v134, v62
	v_add_f32_e32 v177, v177, v63
	v_mfma_f32_32x32x16_bf16 v[2:17], v[190:193], v[50:53], v[2:17]
	v_add_f32_e32 v134, v134, v64
	v_add_f32_e32 v177, v177, v65
	v_cvt_pk_bf16_f32 v58, v58, v59
	v_cvt_pk_bf16_f32 v59, v60, v61
	v_cvt_pk_bf16_f32 v60, v62, v63
	v_cvt_pk_bf16_f32 v61, v64, v65
	v_add_f32_e32 v134, v134, v177
	s_nop 0
	s_waitcnt lgkmcnt(2)
	v_mfma_f32_32x32x16_bf16 v[18:33], v[194:197], v[58:61], v[18:33]
	v_mfma_f32_32x32x16_bf16 v[2:17], v[202:205], v[58:61], v[2:17]
	s_branch .Lmla_nost2

; #define PG8_LAS __attribute__((address_space(3)))
;     DI bf16_t* kv() const { return (bf16_t*)(ws + WS_KV); }
; template <bool MLA> DI void tile_lstore(const TileRegs& R, lbf Ks, lbf Vt, int tid) {
;     constexpr int KLD = MLA ? 104 : 72;
;     const int key = tid >> 3, c = tid & 7;
;     *(PG8_LAS u32x4*)(Ks + key * KLD + 8 * c) = R.k;
;     if (MLA) { if (tid < 256) *(PG8_LAS u32x4*)(Ks + (tid >> 2) * KLD + 64 + 8 * (tid & 3)) = R.k2; }
;     { const int kv = tid & 63, cv = tid >> 6, kp = (kv & ~12) | ((kv & 4) << 1) | ((kv & 8) >> 1);
; #pragma unroll
;       for (int j = 0; j < 8; ++j) Vt[(8 * cv + j) * A_VLD + kp] = (bf16_t)(R.v[j >> 1] >> (16 * (j & 1))); }
; }
; template <bool PV> DI void online_step_mx(f32x16& x0, f32x16& x1, float mx, float& m, float& l, f32x16 (&O)[2]) {
;     const float mn = fmaxf(m, mx), alpha = __builtin_amdgcn_exp2f(m - mn);
;     float ls = 0.f;
; #pragma unroll
;     for (int i = 0; i < 16; ++i) { x0[i] = __builtin_amdgcn_exp2f(x0[i] - mn); x1[i] = __builtin_amdgcn_exp2f(x1[i] - mn); ls += x0[i] + x1[i]; }
;     ls += __shfl_xor(ls, 32);
;     l = l * alpha + ls; m = mn;
;     if (PV) { if (__any(alpha != 1.f)) {
; #pragma unroll
;         for (int i = 0; i < 16; ++i) { O[0][i] *= alpha; O[1][i] *= alpha; } } }
; }
.Lmla_rback_l2:
	v_fma_f32 v34, v34, s40, -v137
	v_fma_f32 v35, v35, s40, -v137
	v_fma_f32 v36, v36, s40, -v137
	v_fma_f32 v37, v37, s40, -v137
	v_exp_f32_e32 v34, v34
	v_exp_f32_e32 v35, v35
	v_exp_f32_e32 v36, v36
	v_exp_f32_e32 v37, v37
	v_fma_f32 v38, v38, s40, -v137
	v_fma_f32 v39, v39, s40, -v137
	v_fma_f32 v40, v40, s40, -v137
	v_fma_f32 v41, v41, s40, -v137
	v_exp_f32_e32 v38, v38
	v_exp_f32_e32 v39, v39
	v_exp_f32_e32 v40, v40
	v_exp_f32_e32 v41, v41
	v_add_f32_e32 v134, v134, v34
	v_add_f32_e32 v134, v134, v36
	v_add_f32_e32 v177, v35, v37
	v_add_f32_e32 v134, v134, v38
	v_add_f32_e32 v177, v177, v39
	v_add_f32_e32 v134, v134, v40
	v_add_f32_e32 v177, v177, v41
	v_cvt_pk_bf16_f32 v34, v34, v35
	v_cvt_pk_bf16_f32 v35, v36, v37
	v_cvt_pk_bf16_f32 v36, v38, v39
	v_cvt_pk_bf16_f32 v37, v40, v41
	s_waitcnt vmcnt(3)
	ds_write_b128 v129, v[106:109] offset:0
	ds_write_b128 v130, v[110:113] offset:128
	ds_write_b16 v131, v102 offset:0
	ds_write_b16_d16_hi v131, v102 offset:144
	v_fma_f32 v42, v42, s40, -v137
	v_fma_f32 v43, v43, s40, -v137
	v_fma_f32 v44, v44, s40, -v137
	v_fma_f32 v45, v45, s40, -v137
	v_exp_f32_e32 v42, v42
	v_exp_f32_e32 v43, v43
	v_exp_f32_e32 v44, v44
	v_exp_f32_e32 v45, v45
	s_waitcnt lgkmcnt(8)
	v_mfma_f32_32x32x16_bf16 v[18:33], v[186:189], v[34:37], v[18:33]
	v_fma_f32 v46, v46, s40, -v137
	v_fma_f32 v47, v47, s40, -v137
	v_fma_f32 v48, v48, s40, -v137
	v_fma_f32 v49, v49, s40, -v137
	v_exp_f32_e32 v46, v46
	v_exp_f32_e32 v47, v47
	v_exp_f32_e32 v48, v48
	v_exp_f32_e32 v49, v49
	v_add_f32_e32 v134, v134, v42
	v_add_f32_e32 v177, v177, v43
	v_add_f32_e32 v134, v134, v44
	v_add_f32_e32 v177, v177, v45
	v_add_f32_e32 v134, v134, v46
	v_add_f32_e32 v177, v177, v47
	v_mfma_f32_32x32x16_bf16 v[2:17], v[190:193], v[34:37], v[2:17]
	ds_read_b128 v[238:241], v136 offset:18528
	ds_read_b128 v[242:245], v136 offset:23136
	v_add_f32_e32 v134, v134, v48
	v_add_f32_e32 v177, v177, v49
	v_cvt_pk_bf16_f32 v42, v42, v43
	v_cvt_pk_bf16_f32 v43, v44, v45
	v_cvt_pk_bf16_f32 v44, v46, v47
	v_cvt_pk_bf16_f32 v45, v48, v49
	ds_write_b16 v131, v103 offset:288
	ds_write_b16_d16_hi v131, v103 offset:432
	ds_write_b16 v131, v104 offset:576
	ds_write_b16_d16_hi v131, v104 offset:720
	v_fma_f32 v50, v50, s40, -v137
	v_fma_f32 v51, v51, s40, -v137
	v_fma_f32 v52, v52, s40, -v137
	v_fma_f32 v53, v53, s40, -v137
	v_exp_f32_e32 v50, v50
	v_exp_f32_e32 v51, v51
	v_exp_f32_e32 v52, v52
	v_exp_f32_e32 v53, v53
	s_waitcnt lgkmcnt(12)
	v_mfma_f32_32x32x16_bf16 v[18:33], v[194:197], v[42:45], v[18:33]
	v_fma_f32 v54, v54, s40, -v137
	v_fma_f32 v55, v55, s40, -v137
	v_fma_f32 v56, v56, s40, -v137
	v_fma_f32 v57, v57, s40, -v137
	v_exp_f32_e32 v54, v54
	v_exp_f32_e32 v55, v55
	v_exp_f32_e32 v56, v56
	v_exp_f32_e32 v57, v57
	v_add_f32_e32 v134, v134, v50
	v_add_f32_e32 v177, v177, v51
	v_add_f32_e32 v134, v134, v52
	v_add_f32_e32 v177, v177, v53
	v_add_f32_e32 v134, v134, v54
	v_add_f32_e32 v177, v177, v55
	v_mfma_f32_32x32x16_bf16 v[2:17], v[202:205], v[42:45], v[2:17]
	v_add_f32_e32 v134, v134, v56
	v_add_f32_e32 v177, v177, v57
	v_cvt_pk_bf16_f32 v50, v50, v51
	v_cvt_pk_bf16_f32 v51, v52, v53
	v_cvt_pk_bf16_f32 v52, v54, v55
	v_cvt_pk_bf16_f32 v53, v56, v57
	ds_write_b16 v131, v105 offset:864
	ds_write_b16_d16_hi v131, v105 offset:1008
	v_fma_f32 v58, v58, s40, -v137
	v_fma_f32 v59, v59, s40, -v137
	v_fma_f32 v60, v60, s40, -v137
	v_fma_f32 v61, v61, s40, -v137
	v_exp_f32_e32 v58, v58
	v_exp_f32_e32 v59, v59
	v_exp_f32_e32 v60, v60
	v_exp_f32_e32 v61, v61
	s_waitcnt lgkmcnt(12)
	v_mfma_f32_32x32x16_bf16 v[18:33], v[210:213], v[50:53], v[18:33]
	v_fma_f32 v62, v62, s40, -v137
	v_fma_f32 v63, v63, s40, -v137
	v_fma_f32 v64, v64, s40, -v137
	v_fma_f32 v65, v65, s40, -v137
	v_exp_f32_e32 v62, v62
	v_exp_f32_e32 v63, v63
	v_exp_f32_e32 v64, v64
	v_exp_f32_e32 v65, v65
	v_add_f32_e32 v134, v134, v58
	v_add_f32_e32 v177, v177, v59
	v_add_f32_e32 v134, v134, v60
	v_add_f32_e32 v177, v177, v61
	v_add_f32_e32 v134, v134, v62
	v_add_f32_e32 v177, v177, v63
	v_mfma_f32_32x32x16_bf16 v[2:17], v[234:237], v[50:53], v[2:17]
	v_add_f32_e32 v134, v134, v64
	v_add_f32_e32 v177, v177, v65
	v_cvt_pk_bf16_f32 v58, v58, v59
	v_cvt_pk_bf16_f32 v59, v60, v61
	v_cvt_pk_bf16_f32 v60, v62, v63
	v_cvt_pk_bf16_f32 v61, v64, v65
	v_add_f32_e32 v134, v134, v177
	s_nop 0
	s_waitcnt lgkmcnt(6)
	v_mfma_f32_32x32x16_bf16 v[18:33], v[238:241], v[58:61], v[18:33]
	v_mfma_f32_32x32x16_bf16 v[2:17], v[242:245], v[58:61], v[2:17]
	s_branch .Lmla_nost2
.Lmla_coop2:
	s_waitcnt vmcnt(3)
	s_add_i32 s24, s17, 2
	s_cmp_lt_i32 s24, s16
	s_cbranch_scc0 .Lmla_nost2
	ds_write_b128 v129, v[106:109] offset:0
	ds_write_b128 v130, v[110:113] offset:128
	ds_write_b16 v131, v102 offset:0
	ds_write_b16_d16_hi v131, v102 offset:144
	ds_write_b16 v131, v103 offset:288
	ds_write_b16_d16_hi v131, v103 offset:432
	ds_write_b16 v131, v104 offset:576
	ds_write_b16_d16_hi v131, v104 offset:720
	ds_write_b16 v131, v105 offset:864
	ds_write_b16_d16_hi v131, v105 offset:1008

; #define PG8_LAS __attribute__((address_space(3)))
;     DI bf16_t* kv() const { return (bf16_t*)(ws + WS_KV); }
; template <bool MLA> DI void tile_lstore(const TileRegs& R, lbf Ks, lbf Vt, int tid) {
;     constexpr int KLD = MLA ? 104 : 72;
;     const int key = tid >> 3, c = tid & 7;
;     *(PG8_LAS u32x4*)(Ks + key * KLD + 8 * c) = R.k;
;     if (MLA) { if (tid < 256) *(PG8_LAS u32x4*)(Ks + (tid >> 2) * KLD + 64 + 8 * (tid & 3)) = R.k2; }
;     { const int kv = tid & 63, cv = tid >> 6, kp = (kv & ~12) | ((kv & 4) << 1) | ((kv & 8) >> 1);
; #pragma unroll
;       for (int j = 0; j < 8; ++j) Vt[(8 * cv + j) * A_VLD + kp] = (bf16_t)(R.v[j >> 1] >> (16 * (j & 1))); }
; }
; template <bool PV> DI void online_step_mx(f32x16& x0, f32x16& x1, float mx, float& m, float& l, f32x16 (&O)[2]) {
;     const float mn = fmaxf(m, mx), alpha = __builtin_amdgcn_exp2f(m - mn);
;     float ls = 0.f;
; #pragma unroll
;     for (int i = 0; i < 16; ++i) { x0[i] = __builtin_amdgcn_exp2f(x0[i] - mn); x1[i] = __builtin_amdgcn_exp2f(x1[i] - mn); ls += x0[i] + x1[i]; }
;     ls += __shfl_xor(ls, 32);
;     l = l * alpha + ls; m = mn;
;     if (PV) { if (__any(alpha != 1.f)) {
; #pragma unroll
;         for (int i = 0; i < 16; ++i) { O[0][i] *= alpha; O[1][i] *= alpha; } } }
; }
.Lmla_rback_f3:
	v_fma_f32 v138, v138, s40, -v137
	v_fma_f32 v139, v139, s40, -v137
	v_fma_f32 v140, v140, s40, -v137
	v_fma_f32 v141, v141, s40, -v137
	s_waitcnt lgkmcnt(4)
	v_mfma_f32_32x32x16_bf16 v[34:49], v[210:213], v[74:77], v[34:49]
	v_exp_f32_e32 v138, v138
	v_exp_f32_e32 v139, v139
	v_exp_f32_e32 v140, v140
	v_exp_f32_e32 v141, v141
	v_fma_f32 v142, v142, s40, -v137
	v_fma_f32 v143, v143, s40, -v137
	v_fma_f32 v144, v144, s40, -v137
	v_mfma_f32_32x32x16_bf16 v[50:65], v[234:237], v[74:77], v[50:65]
	ds_read_b128 v[194:197], v135 offset:160
	ds_read_b128 v[202:205], v135 offset:6816
	v_fma_f32 v145, v145, s40, -v137
	v_exp_f32_e32 v142, v142
	v_exp_f32_e32 v143, v143
	v_exp_f32_e32 v144, v144
	v_exp_f32_e32 v145, v145
	v_add_f32_e32 v134, v134, v138
	s_waitcnt lgkmcnt(4)
	v_mfma_f32_32x32x16_bf16 v[34:49], v[238:241], v[78:81], v[34:49]
	v_add_f32_e32 v134, v134, v140
	v_add_f32_e32 v177, v139, v141
	v_add_f32_e32 v134, v134, v142
	v_add_f32_e32 v177, v177, v143
	v_add_f32_e32 v134, v134, v144
	v_add_f32_e32 v177, v177, v145
	v_cvt_pk_bf16_f32 v138, v138, v139
	v_mfma_f32_32x32x16_bf16 v[50:65], v[242:245], v[78:81], v[50:65]
	ds_read_b128 v[210:213], v136 offset:27648
	ds_read_b128 v[234:237], v136 offset:32256
	v_cvt_pk_bf16_f32 v139, v140, v141
	v_cvt_pk_bf16_f32 v140, v142, v143
	v_cvt_pk_bf16_f32 v141, v144, v145
	s_waitcnt vmcnt(3)
	ds_write_b128 v129, v[86:89] offset:13312
	ds_write_b128 v130, v[90:93] offset:13440
	ds_write_b16 v131, v82 offset:9216
	ds_write_b16_d16_hi v131, v82 offset:9360
	v_fma_f32 v146, v146, s40, -v137
	v_fma_f32 v147, v147, s40, -v137
	v_fma_f32 v148, v148, s40, -v137
	v_fma_f32 v149, v149, s40, -v137
	s_waitcnt lgkmcnt(8)
	v_mfma_f32_32x32x16_bf16 v[34:49], v[186:189], v[94:97], v[34:49]
	v_exp_f32_e32 v146, v146
	v_exp_f32_e32 v147, v147
	v_exp_f32_e32 v148, v148
	v_exp_f32_e32 v149, v149
	v_fma_f32 v150, v150, s40, -v137
	v_fma_f32 v151, v151, s40, -v137
	v_fma_f32 v152, v152, s40, -v137
	v_mfma_f32_32x32x16_bf16 v[50:65], v[190:193], v[94:97], v[50:65]
	ds_read_b128 v[238:241], v136 offset:27680
	ds_read_b128 v[242:245], v136 offset:32288
	v_fma_f32 v153, v153, s40, -v137
	v_exp_f32_e32 v150, v150
	v_exp_f32_e32 v151, v151
	v_exp_f32_e32 v152, v152
	v_exp_f32_e32 v153, v153
	v_add_f32_e32 v134, v134, v146
	v_add_f32_e32 v177, v177, v147
	s_waitcnt lgkmcnt(8)
	v_mfma_f32_32x32x16_bf16 v[34:49], v[194:197], v[98:101], v[34:49]
	v_add_f32_e32 v134, v134, v148
	v_add_f32_e32 v177, v177, v149
	v_add_f32_e32 v134, v134, v150
	v_add_f32_e32 v177, v177, v151
	v_add_f32_e32 v134, v134, v152
	v_add_f32_e32 v177, v177, v153
	v_cvt_pk_bf16_f32 v146, v146, v147
	v_mfma_f32_32x32x16_bf16 v[50:65], v[202:205], v[98:101], v[50:65]
	ds_read_b128 v[186:189], v136 offset:27712
	ds_read_b128 v[190:193], v136 offset:32320
	v_cvt_pk_bf16_f32 v147, v148, v149
	v_cvt_pk_bf16_f32 v148, v150, v151
	v_cvt_pk_bf16_f32 v149, v152, v153
	ds_write_b16 v131, v83 offset:9504
	ds_write_b16_d16_hi v131, v83 offset:9648
	ds_write_b16 v131, v84 offset:9792
	ds_write_b16_d16_hi v131, v84 offset:9936
	v_fma_f32 v154, v154, s40, -v137
	v_fma_f32 v155, v155, s40, -v137
	v_fma_f32 v156, v156, s40, -v137
	v_fma_f32 v157, v157, s40, -v137
	s_waitcnt lgkmcnt(12)
	v_mfma_f32_32x32x16_bf16 v[18:33], v[210:213], v[138:141], v[18:33]
	v_exp_f32_e32 v154, v154
	v_exp_f32_e32 v155, v155
	v_exp_f32_e32 v156, v156
	v_exp_f32_e32 v157, v157
	v_fma_f32 v158, v158, s40, -v137
	v_fma_f32 v159, v159, s40, -v137
	v_fma_f32 v160, v160, s40, -v137
	v_mfma_f32_32x32x16_bf16 v[2:17], v[234:237], v[138:141], v[2:17]
	ds_read_b128 v[194:197], v136 offset:27744
	ds_read_b128 v[202:205], v136 offset:32352
	v_fma_f32 v161, v161, s40, -v137
	v_exp_f32_e32 v158, v158
	v_exp_f32_e32 v159, v159
	v_exp_f32_e32 v160, v160
	v_exp_f32_e32 v161, v161
	v_add_f32_e32 v134, v134, v154
	v_add_f32_e32 v177, v177, v155
	s_waitcnt lgkmcnt(8)
	v_mfma_f32_32x32x16_bf16 v[18:33], v[238:241], v[146:149], v[18:33]
	v_add_f32_e32 v134, v134, v156
	v_add_f32_e32 v177, v177, v157
	v_add_f32_e32 v134, v134, v158
	v_add_f32_e32 v177, v177, v159
	v_add_f32_e32 v134, v134, v160
	v_add_f32_e32 v177, v177, v161
	v_cvt_pk_bf16_f32 v154, v154, v155
	v_mfma_f32_32x32x16_bf16 v[2:17], v[242:245], v[146:149], v[2:17]
	v_cvt_pk_bf16_f32 v155, v156, v157
	v_cvt_pk_bf16_f32 v156, v158, v159
	v_cvt_pk_bf16_f32 v157, v160, v161
	ds_write_b16 v131, v85 offset:10080
	ds_write_b16_d16_hi v131, v85 offset:10224
	v_fma_f32 v162, v162, s40, -v137
	v_fma_f32 v163, v163, s40, -v137
	v_fma_f32 v164, v164, s40, -v137
	v_fma_f32 v165, v165, s40, -v137
	v_exp_f32_e32 v162, v162
	v_exp_f32_e32 v163, v163
	v_exp_f32_e32 v164, v164
	v_exp_f32_e32 v165, v165
	s_waitcnt lgkmcnt(8)
	v_mfma_f32_32x32x16_bf16 v[18:33], v[186:189], v[154:157], v[18:33]
	v_fma_f32 v166, v166, s40, -v137
	v_fma_f32 v167, v167, s40, -v137
	v_fma_f32 v168, v168, s40, -v137
	v_fma_f32 v169, v169, s40, -v137
	v_exp_f32_e32 v166, v166
	v_exp_f32_e32 v167, v167
	v_exp_f32_e32 v168, v168
	v_exp_f32_e32 v169, v169
	v_add_f32_e32 v134, v134, v162
	v_add_f32_e32 v177, v177, v163
	v_add_f32_e32 v134, v134, v164
	v_add_f32_e32 v177, v177, v165
	v_add_f32_e32 v134, v134, v166
	v_add_f32_e32 v177, v177, v167
	v_mfma_f32_32x32x16_bf16 v[2:17], v[190:193], v[154:157], v[2:17]
	v_add_f32_e32 v134, v134, v168
	v_add_f32_e32 v177, v177, v169
	v_cvt_pk_bf16_f32 v162, v162, v163
	v_cvt_pk_bf16_f32 v163, v164, v165
	v_cvt_pk_bf16_f32 v164, v166, v167
	v_cvt_pk_bf16_f32 v165, v168, v169
	v_add_f32_e32 v134, v134, v177
	s_nop 0
	s_waitcnt lgkmcnt(2)
	v_mfma_f32_32x32x16_bf16 v[18:33], v[194:197], v[162:165], v[18:33]
	v_mfma_f32_32x32x16_bf16 v[2:17], v[202:205], v[162:165], v[2:17]
	s_branch .Lmla_nost3

; #define PG8_LAS __attribute__((address_space(3)))
;     DI bf16_t* kv() const { return (bf16_t*)(ws + WS_KV); }
; template <bool MLA> DI void tile_lstore(const TileRegs& R, lbf Ks, lbf Vt, int tid) {
;     constexpr int KLD = MLA ? 104 : 72;
;     const int key = tid >> 3, c = tid & 7;
;     *(PG8_LAS u32x4*)(Ks + key * KLD + 8 * c) = R.k;
;     if (MLA) { if (tid < 256) *(PG8_LAS u32x4*)(Ks + (tid >> 2) * KLD + 64 + 8 * (tid & 3)) = R.k2; }
;     { const int kv = tid & 63, cv = tid >> 6, kp = (kv & ~12) | ((kv & 4) << 1) | ((kv & 8) >> 1);
; #pragma unroll
;       for (int j = 0; j < 8; ++j) Vt[(8 * cv + j) * A_VLD + kp] = (bf16_t)(R.v[j >> 1] >> (16 * (j & 1))); }
; }
; template <bool PV> DI void online_step_mx(f32x16& x0, f32x16& x1, float mx, float& m, float& l, f32x16 (&O)[2]) {
;     const float mn = fmaxf(m, mx), alpha = __builtin_amdgcn_exp2f(m - mn);
;     float ls = 0.f;
; #pragma unroll
;     for (int i = 0; i < 16; ++i) { x0[i] = __builtin_amdgcn_exp2f(x0[i] - mn); x1[i] = __builtin_amdgcn_exp2f(x1[i] - mn); ls += x0[i] + x1[i]; }
;     ls += __shfl_xor(ls, 32);
;     l = l * alpha + ls; m = mn;
;     if (PV) { if (__any(alpha != 1.f)) {
; #pragma unroll
;         for (int i = 0; i < 16; ++i) { O[0][i] *= alpha; O[1][i] *= alpha; } } }
; }
.Lmla_rback_l3:
	v_fma_f32 v138, v138, s40, -v137
	v_fma_f32 v139, v139, s40, -v137
	v_fma_f32 v140, v140, s40, -v137
	v_fma_f32 v141, v141, s40, -v137
	v_exp_f32_e32 v138, v138
	v_exp_f32_e32 v139, v139
	v_exp_f32_e32 v140, v140
	v_exp_f32_e32 v141, v141
	v_fma_f32 v142, v142, s40, -v137
	v_fma_f32 v143, v143, s40, -v137
	v_fma_f32 v144, v144, s40, -v137
	v_fma_f32 v145, v145, s40, -v137
	v_exp_f32_e32 v142, v142
	v_exp_f32_e32 v143, v143
	v_exp_f32_e32 v144, v144
	v_exp_f32_e32 v145, v145
	v_add_f32_e32 v134, v134, v138
	v_add_f32_e32 v134, v134, v140
	v_add_f32_e32 v177, v139, v141
	v_add_f32_e32 v134, v134, v142
	v_add_f32_e32 v177, v177, v143
	v_add_f32_e32 v134, v134, v144
	v_add_f32_e32 v177, v177, v145
	v_cvt_pk_bf16_f32 v138, v138, v139
	v_cvt_pk_bf16_f32 v139, v140, v141
	v_cvt_pk_bf16_f32 v140, v142, v143
	v_cvt_pk_bf16_f32 v141, v144, v145
	s_waitcnt vmcnt(3)
	ds_write_b128 v129, v[86:89] offset:13312
	ds_write_b128 v130, v[90:93] offset:13440
	ds_write_b16 v131, v82 offset:9216
	ds_write_b16_d16_hi v131, v82 offset:9360
	v_fma_f32 v146, v146, s40, -v137
	v_fma_f32 v147, v147, s40, -v137
	v_fma_f32 v148, v148, s40, -v137
	v_fma_f32 v149, v149, s40, -v137
	v_exp_f32_e32 v146, v146
	v_exp_f32_e32 v147, v147
	v_exp_f32_e32 v148, v148
	v_exp_f32_e32 v149, v149
	s_waitcnt lgkmcnt(8)
	v_mfma_f32_32x32x16_bf16 v[18:33], v[186:189], v[138:141], v[18:33]
	v_fma_f32 v150, v150, s40, -v137
	v_fma_f32 v151, v151, s40, -v137
	v_fma_f32 v152, v152, s40, -v137
	v_fma_f32 v153, v153, s40, -v137
	v_exp_f32_e32 v150, v150
	v_exp_f32_e32 v151, v151
	v_exp_f32_e32 v152, v152
	v_exp_f32_e32 v153, v153
	v_add_f32_e32 v134, v134, v146
	v_add_f32_e32 v177, v177, v147
	v_add_f32_e32 v134, v134, v148
	v_add_f32_e32 v177, v177, v149
	v_add_f32_e32 v134, v134, v150
	v_add_f32_e32 v177, v177, v151
	v_mfma_f32_32x32x16_bf16 v[2:17], v[190:193], v[138:141], v[2:17]
	ds_read_b128 v[238:241], v136 offset:27744
	ds_read_b128 v[242:245], v136 offset:32352
	v_add_f32_e32 v134, v134, v152
	v_add_f32_e32 v177, v177, v153
	v_cvt_pk_bf16_f32 v146, v146, v147
	v_cvt_pk_bf16_f32 v147, v148, v149
	v_cvt_pk_bf16_f32 v148, v150, v151
	v_cvt_pk_bf16_f32 v149, v152, v153
	ds_write_b16 v131, v83 offset:9504
	ds_write_b16_d16_hi v131, v83 offset:9648
	ds_write_b16 v131, v84 offset:9792
	ds_write_b16_d16_hi v131, v84 offset:9936
	v_fma_f32 v154, v154, s40, -v137
	v_fma_f32 v155, v155, s40, -v137
	v_fma_f32 v156, v156, s40, -v137
	v_fma_f32 v157, v157, s40, -v137
	v_exp_f32_e32 v154, v154
	v_exp_f32_e32 v155, v155
	v_exp_f32_e32 v156, v156
	v_exp_f32_e32 v157, v157
	s_waitcnt lgkmcnt(12)
	v_mfma_f32_32x32x16_bf16 v[18:33], v[194:197], v[146:149], v[18:33]
	v_fma_f32 v158, v158, s40, -v137
	v_fma_f32 v159, v159, s40, -v137
	v_fma_f32 v160, v160, s40, -v137
	v_fma_f32 v161, v161, s40, -v137
	v_exp_f32_e32 v158, v158
	v_exp_f32_e32 v159, v159
	v_exp_f32_e32 v160, v160
	v_exp_f32_e32 v161, v161
	v_add_f32_e32 v134, v134, v154
	v_add_f32_e32 v177, v177, v155
	v_add_f32_e32 v134, v134, v156
	v_add_f32_e32 v177, v177, v157
	v_add_f32_e32 v134, v134, v158
	v_add_f32_e32 v177, v177, v159
	v_mfma_f32_32x32x16_bf16 v[2:17], v[202:205], v[146:149], v[2:17]
	v_add_f32_e32 v134, v134, v160
	v_add_f32_e32 v177, v177, v161
	v_cvt_pk_bf16_f32 v154, v154, v155
	v_cvt_pk_bf16_f32 v155, v156, v157
	v_cvt_pk_bf16_f32 v156, v158, v159
	v_cvt_pk_bf16_f32 v157, v160, v161
	ds_write_b16 v131, v85 offset:10080
	ds_write_b16_d16_hi v131, v85 offset:10224
	v_fma_f32 v162, v162, s40, -v137
	v_fma_f32 v163, v163, s40, -v137
	v_fma_f32 v164, v164, s40, -v137
	v_fma_f32 v165, v165, s40, -v137
	v_exp_f32_e32 v162, v162
	v_exp_f32_e32 v163, v163
	v_exp_f32_e32 v164, v164
	v_exp_f32_e32 v165, v165
	s_waitcnt lgkmcnt(12)
	v_mfma_f32_32x32x16_bf16 v[18:33], v[210:213], v[154:157], v[18:33]
	v_fma_f32 v166, v166, s40, -v137
	v_fma_f32 v167, v167, s40, -v137
	v_fma_f32 v168, v168, s40, -v137
	v_fma_f32 v169, v169, s40, -v137
	v_exp_f32_e32 v166, v166
	v_exp_f32_e32 v167, v167
	v_exp_f32_e32 v168, v168
	v_exp_f32_e32 v169, v169
	v_add_f32_e32 v134, v134, v162
	v_add_f32_e32 v177, v177, v163
	v_add_f32_e32 v134, v134, v164
	v_add_f32_e32 v177, v177, v165
	v_add_f32_e32 v134, v134, v166
	v_add_f32_e32 v177, v177, v167
	v_mfma_f32_32x32x16_bf16 v[2:17], v[234:237], v[154:157], v[2:17]
	v_add_f32_e32 v134, v134, v168
	v_add_f32_e32 v177, v177, v169
	v_cvt_pk_bf16_f32 v162, v162, v163
	v_cvt_pk_bf16_f32 v163, v164, v165
	v_cvt_pk_bf16_f32 v164, v166, v167
	v_cvt_pk_bf16_f32 v165, v168, v169
	v_add_f32_e32 v134, v134, v177
	s_nop 0
	s_waitcnt lgkmcnt(6)
	v_mfma_f32_32x32x16_bf16 v[18:33], v[238:241], v[162:165], v[18:33]
	v_mfma_f32_32x32x16_bf16 v[2:17], v[242:245], v[162:165], v[2:17]
	s_branch .Lmla_nost3
.Lmla_coop3:
	s_waitcnt vmcnt(3)
	s_add_i32 s24, s17, 2
	s_cmp_lt_i32 s24, s16
	s_cbranch_scc0 .Lmla_nost3
	ds_write_b128 v129, v[86:89] offset:13312
	ds_write_b128 v130, v[90:93] offset:13440
	ds_write_b16 v131, v82 offset:9216
	ds_write_b16_d16_hi v131, v82 offset:9360
	ds_write_b16 v131, v83 offset:9504
	ds_write_b16_d16_hi v131, v83 offset:9648
	ds_write_b16 v131, v84 offset:9792
	ds_write_b16_d16_hi v131, v84 offset:9936
	ds_write_b16 v131, v85 offset:10080
	ds_write_b16_d16_hi v131, v85 offset:10224
